# P6 conv: the same mul+add to fma fusion also in the section in front of the main loop (56 more packed multiplies removed)
# speedup vs baseline: 1.0089x; 1.0089x over previous
; __device__ __forceinline__ float silu_f(float x) { return x * __builtin_amdgcn_rcpf(1.0f + __builtin_amdgcn_exp2f(-1.4426950408889634f * x)); }
; __device__ __forceinline__ float bflo(unsigned x) { return __uint_as_float(x << 16); }
; __device__ __forceinline__ float bfhi(unsigned x) { return __uint_as_float(x & 0xffff0000u); }
; __device__ __forceinline__ unsigned pk2(float lo, float hi) { return pg8::cvt_pk_bf16(lo, hi); }
; __device__ __forceinline__ float silu_f(float x) { return x * __builtin_amdgcn_rcpf(1.0f + __builtin_amdgcn_exp2f(-1.4426950408889634f * x)); }
; __device__ __forceinline__ void ph_conv(const bf16* XBC, const float* state_conv, const float* conv_w, const float* conv_b, bf16* XT, bf16* BN, bf16* CN, bf16* BT, int c_lo, int c_hi, int vcu, int G, int tid) {
;     ...
;         for (int t8 = 0; t8 < 2; ++t8) {
;             float y0[8], y1[8];
; #pragma unroll
;             for (int i = 0; i < 8; ++i) { const float x0 = bflo(raw[3 + t8 * 8 + i]), x1 = bfhi(raw[3 + t8 * 8 + i]);
;                 const float a0 = b0 + w0[0] * p0[0] + w0[1] * p0[1] + w0[2] * p0[2] + w0[3] * x0, a1 = b1 + w1[0] * p1[0] + w1[1] * p1[1] + w1[2] * p1[2] + w1[3] * x1;
;                 y0[i] = silu_f(a0); y1[i] = silu_f(a1); p0[0] = p0[1]; p0[1] = p0[2]; p0[2] = x0; p1[0] = p1[1]; p1[1] = p1[2]; p1[2] = x1; }
;             v4u t0, t1; t0.x = pk2(y0[0], y0[1]); t0.y = pk2(y0[2], y0[3]); t0.z = pk2(y0[4], y0[5]); t0.w = pk2(y0[6], y0[7]);
;             t1.x = pk2(y1[0], y1[1]); t1.y = pk2(y1[2], y1[3]); t1.z = pk2(y1[4], y1[5]); t1.w = pk2(y1[6], y1[7]);
;             const int tl = q * 16 + t8 * 8;
;             if (tid < 256) { const int h = ch >> 6, p = ch & 63; bf16* d = XT + ((size_t)(ci * 8 + h) * 64 + p) * 64 + tl; *(v4u*)d = t0; *(v4u*)(d + 64) = t1; }
.LBB0_801:
	v_lshlrev_b32_e32 v80, 16, v0
	v_and_b32_e32 v82, 0xffff0000, v0
	v_fma_f32 v0, v14, v6, v18
	v_mov_b32_e32 v81, v5
	v_fma_f32 v0, v15, v7, v0
	v_mov_b32_e32 v83, v1
	v_fma_f32 v0, v11, v81, v0
	v_fma_f32 v6, v10, v80, v0
	s_ashr_i32 s37, s22, 2
	v_fma_f32 v0, v36, v2, v19
	v_fma_f32 v0, v37, v3, v0
	v_lshl_add_u32 v38, s37, 1, v50
	v_fma_f32 v0, v33, v83, v0
	v_fma_f32 v2, v32, v82, v0
	v_mul_f32_e32 v0, 0xbfb8aa3b, v6
	v_exp_f32_e32 v0, v0
	v_mul_f32_e32 v4, 0xbfb8aa3b, v2
	v_exp_f32_e32 v4, v4
	v_ashrrev_i32_e32 v39, 31, v38
	v_add_f32_e32 v0, 1.0, v0
	v_rcp_f32_e32 v47, v0
	v_add_f32_e32 v0, 1.0, v4
	v_mov_b32_e32 v4, v7
	v_rcp_f32_e32 v49, v0
	v_fma_f32 v4, v14, v4, v18
	v_fma_f32 v79, v15, v5, v4
	v_lshlrev_b32_e32 v5, 16, v46
	v_mov_b32_e32 v0, v3
	v_mul_f32_e32 v48, v6, v47
	v_mov_b32_e32 v6, v5
	v_mov_b32_e32 v7, v80
	v_and_b32_e32 v3, 0xffff0000, v46
	v_mul_f32_e32 v49, v2, v49
	v_and_b32_e32 v2, 0xffff0000, v41
	v_fma_f32 v0, v36, v0, v19
	v_lshlrev_b32_e32 v4, 16, v41
	v_fma_f32 v41, v11, v7, v79
	v_fma_f32 v84, v37, v1, v0
	v_fma_f32 v41, v10, v6, v41
	v_fma_f32 v1, v35, v81, v18
	v_mul_f32_e32 v46, 0xbfb8aa3b, v41
	v_fma_f32 v81, v34, v80, v1
	v_exp_f32_e32 v79, v46
	v_fma_f32 v47, v11, v5, v81
	v_fma_f32 v46, v10, v4, v47
	v_mul_f32_e32 v47, 0xbfb8aa3b, v46
	v_exp_f32_e32 v47, v47
	v_fma_f32 v1, v31, v83, v19
	v_fma_f32 v81, v30, v82, v1
	v_add_f32_e32 v0, 1.0, v79
	v_rcp_f32_e32 v79, v0
	v_add_f32_e32 v0, 1.0, v47
	v_rcp_f32_e32 v47, v0
	v_mul_f32_e32 v80, v41, v79
	v_fma_f32 v7, v35, v7, v18
	v_fma_f32 v83, v34, v6, v7
	v_mov_b32_e32 v6, v3
	v_mov_b32_e32 v7, v82
	v_mul_f32_e32 v79, v46, v47
	v_pk_mul_f32 v[46:47], v[32:33], v[6:7]
	v_add_f32_e32 v41, v47, v84
	v_add_f32_e32 v41, v46, v41
	v_mul_f32_e32 v46, 0xbfb8aa3b, v41
	v_exp_f32_e32 v82, v46
	v_fma_f32 v7, v31, v7, v19
	v_fma_f32 v47, v33, v3, v81
	v_fma_f32 v81, v32, v2, v47
	v_mul_f32_e32 v46, 0xbfb8aa3b, v81
	v_exp_f32_e32 v84, v46
	v_fma_f32 v87, v30, v6, v7
	v_add_f32_e32 v82, 1.0, v82
	v_add_f32_e32 v84, 1.0, v84
	v_fma_f32 v7, v31, v3, v19
	v_rcp_f32_e32 v82, v82
	v_rcp_f32_e32 v85, v84
	v_fma_f32 v47, v35, v5, v18
	v_fma_f32 v88, v30, v2, v7
	v_lshlrev_b32_e32 v7, 16, v40
	v_fma_f32 v86, v34, v4, v47
	v_mov_b32_e32 v46, v4
	v_mov_b32_e32 v47, v7
	v_mul_f32_e32 v84, v41, v82
	v_fma_f32 v6, v12, v46, v83
	v_mul_f32_e32 v82, v81, v85
	v_fma_f32 v81, v13, v47, v6
	v_mul_f32_e32 v6, 0xbfb8aa3b, v81
	v_exp_f32_e32 v46, v6
	v_lshlrev_b32_e32 v6, 16, v45
	v_and_b32_e32 v0, 0xffff0000, v45
	v_pk_mov_b32 v[4:5], v[6:7], v[4:5] op_sel:[1,0]
	v_add_f32_e32 v45, 1.0, v46
	v_fma_f32 v47, v11, v7, v86
	v_fma_f32 v46, v10, v6, v47
	v_mul_f32_e32 v47, 0xbfb8aa3b, v46
	v_and_b32_e32 v41, 0xffff0000, v43
	v_lshlrev_b32_e32 v43, 16, v43
	v_exp_f32_e32 v47, v47
	v_fma_f32 v5, v35, v5, v18
	v_fma_f32 v83, v34, v4, v5
	v_mov_b32_e32 v4, v6
	v_mov_b32_e32 v5, v43
	v_add_f32_e32 v47, 1.0, v47
	v_fma_f32 v4, v12, v4, v83
	v_fma_f32 v4, v13, v5, v4
	v_mul_f32_e32 v5, 0xbfb8aa3b, v4
	v_rcp_f32_e32 v47, v47
	v_exp_f32_e32 v5, v5
	v_and_b32_e32 v1, 0xffff0000, v40
	v_rcp_f32_e32 v45, v45
	v_mul_f32_e32 v83, v46, v47
	v_mov_b32_e32 v46, v2
	v_mov_b32_e32 v47, v1
	v_add_f32_e32 v5, 1.0, v5
	v_rcp_f32_e32 v5, v5
	v_fma_f32 v46, v28, v46, v87
	v_fma_f32 v86, v29, v47, v46
	v_mul_f32_e32 v46, 0xbfb8aa3b, v86
	v_exp_f32_e32 v87, v46
	v_mul_f32_e32 v85, v81, v45
	v_mul_f32_e32 v81, v4, v5
	v_pk_mov_b32 v[2:3], v[0:1], v[2:3] op_sel:[1,0]
	v_and_b32_e32 v40, 0xffff0000, v42
	v_lshlrev_b32_e32 v42, 16, v42
	v_fma_f32 v5, v35, v7, v18
	v_fma_f32 v45, v34, v6, v5
	v_fma_f32 v3, v31, v3, v19
	v_fma_f32 v5, v11, v43, v45
	v_add_f32_e32 v45, 1.0, v87
	v_fma_f32 v87, v30, v2, v3
	v_mov_b32_e32 v2, v0
	v_mov_b32_e32 v3, v41
	v_fma_f32 v2, v28, v2, v87
	v_fma_f32 v47, v33, v1, v88
	v_fma_f32 v88, v29, v3, v2
	v_mul_f32_e32 v2, 0xbfb8aa3b, v88
	v_exp_f32_e32 v2, v2
	v_rcp_f32_e32 v45, v45
	v_fma_f32 v4, v10, v42, v5
	v_fma_f32 v46, v32, v0, v47
	v_add_f32_e32 v2, 1.0, v2
	v_rcp_f32_e32 v5, v2
	v_mul_f32_e32 v47, 0xbfb8aa3b, v46
	v_fma_f32 v3, v31, v1, v19
	v_mul_f32_e32 v90, v86, v45
	v_fma_f32 v45, v30, v0, v3
	v_exp_f32_e32 v47, v47
	v_fma_f32 v3, v33, v41, v45
	v_fma_f32 v89, v32, v40, v3
	v_mul_f32_e32 v2, 0xbfb8aa3b, v4
	v_exp_f32_e32 v2, v2
	v_mul_f32_e32 v3, 0xbfb8aa3b, v89
	v_exp_f32_e32 v3, v3
	v_add_f32_e32 v47, 1.0, v47
	v_rcp_f32_e32 v47, v47
	v_add_f32_e32 v2, 1.0, v2
	v_mul_f32_e32 v86, v88, v5
	v_rcp_f32_e32 v5, v2
	v_add_f32_e32 v88, 1.0, v3
	v_pk_mov_b32 v[2:3], v[42:43], v[6:7] op_sel:[1,0]
	v_mul_f32_e32 v87, v46, v47
	v_lshlrev_b32_e32 v47, 16, v44
	v_fma_f32 v3, v35, v3, v18
	v_mov_b32_e32 v46, v42
	v_pk_mov_b32 v[0:1], v[40:41], v[0:1] op_sel:[1,0]
	v_fma_f32 v6, v34, v2, v3
	v_and_b32_e32 v45, 0xffff0000, v44
	v_fma_f32 v2, v12, v46, v6
	v_fma_f32 v1, v31, v1, v19
	v_mov_b32_e32 v44, v40
	v_fma_f32 v2, v13, v47, v2
	v_fma_f32 v3, v30, v0, v1
	v_rcp_f32_e32 v6, v88
	v_fma_f32 v0, v28, v44, v3
	v_fma_f32 v0, v29, v45, v0
	v_mul_f32_e32 v1, 0xbfb8aa3b, v2
	v_mul_f32_e32 v3, 0xbfb8aa3b, v0
	v_exp_f32_e32 v1, v1
	v_exp_f32_e32 v3, v3
	s_lshl_b32 s18, s37, 6
	s_and_b32 s36, s33, 48
	v_add_f32_e32 v1, 1.0, v1
	v_add_f32_e32 v3, 1.0, v3
	v_rcp_f32_e32 v1, v1
	v_rcp_f32_e32 v3, v3
	v_lshlrev_b64 v[38:39], 14, v[38:39]
	s_or_b32 s22, s18, s36
	v_lshl_add_u64 v[38:39], v[24:25], 0, v[38:39]
	v_mul_f32_e32 v88, v4, v5
	v_mul_f32_e32 v89, v89, v6
	v_mul_f32_e32 v44, v2, v1
	v_mul_f32_e32 v46, v0, v3
	v_cvt_pk_bf16_f32 v0, v48, v80
	v_cvt_pk_bf16_f32 v1, v79, v85
	v_cvt_pk_bf16_f32 v2, v83, v81
	v_cvt_pk_bf16_f32 v3, v88, v44
	v_cvt_pk_bf16_f32 v4, v49, v84
	v_cvt_pk_bf16_f32 v5, v82, v90
	v_cvt_pk_bf16_f32 v6, v87, v86
	v_cvt_pk_bf16_f32 v7, v89, v46
	s_and_saveexec_b64 s[24:25], s[2:3]
	s_xor_b64 s[24:25], exec, s[24:25]
	s_cbranch_execz .LBB0_807
; __device__ __forceinline__ unsigned pk2(float lo, float hi) { return pg8::cvt_pk_bf16(lo, hi); }
; __device__ __forceinline__ void ph_conv(const bf16* XBC, const float* state_conv, const float* conv_w, const float* conv_b, bf16* XT, bf16* BN, bf16* CN, bf16* BT, int c_lo, int c_hi, int vcu, int G, int tid) {
;     ...
;             else if (tid < 384) { const int cb = ch - 512, g = cb >> 7, n = cb & 127;
; #pragma unroll
;                 for (int i = 0; i < 8; ++i) *(unsigned*)(BN + (size_t)(row0 + t8 * 8 + i) * 256 + cb) = pk2(y0[i], y1[i]);
;                 bf16* d = BT + ((size_t)(ci * 2 + g) * 128 + n) * 64 + tl; *(v4u*)d = t0; *(v4u*)(d + 64) = t1; }
;             else { const int cc = ch - 768;
; #pragma unroll
;                 for (int i = 0; i < 8; ++i) *(unsigned*)(CN + (size_t)(row0 + t8 * 8 + i) * 256 + cc) = pk2(y0[i], y1[i]); }
	s_ashr_i32 s23, s22, 31
	s_lshl_b64 s[26:27], s[22:23], 9
	s_and_saveexec_b64 s[28:29], s[4:5]
	s_xor_b64 s[28:29], exec, s[28:29]
	s_cbranch_execz .LBB0_804
	s_or_b32 s38, s22, 1
	s_ashr_i32 s39, s38, 31
	v_lshl_add_u64 v[0:1], v[20:21], 0, s[26:27]
	s_lshl_b64 s[38:39], s[38:39], 9
	v_cvt_pk_bf16_f32 v2, v48, v49
	global_store_dword v[0:1], v2, off offset:-1536
	v_lshl_add_u64 v[0:1], v[20:21], 0, s[38:39]
	s_or_b32 s38, s22, 2
	s_ashr_i32 s39, s38, 31
	s_lshl_b64 s[38:39], s[38:39], 9
	v_cvt_pk_bf16_f32 v2, v80, v84
	global_store_dword v[0:1], v2, off offset:-1536
	v_lshl_add_u64 v[0:1], v[20:21], 0, s[38:39]
	s_or_b32 s38, s22, 3
	s_ashr_i32 s39, s38, 31
	s_lshl_b64 s[38:39], s[38:39], 9
	v_cvt_pk_bf16_f32 v2, v79, v82
	global_store_dword v[0:1], v2, off offset:-1536
	v_lshl_add_u64 v[0:1], v[20:21], 0, s[38:39]
	s_or_b32 s38, s22, 4
	s_ashr_i32 s39, s38, 31
	s_lshl_b64 s[38:39], s[38:39], 9
	v_cvt_pk_bf16_f32 v2, v85, v90
	global_store_dword v[0:1], v2, off offset:-1536
	v_lshl_add_u64 v[0:1], v[20:21], 0, s[38:39]
	s_or_b32 s38, s22, 5
	s_ashr_i32 s39, s38, 31
	s_lshl_b64 s[38:39], s[38:39], 9
	v_cvt_pk_bf16_f32 v2, v83, v87
	global_store_dword v[0:1], v2, off offset:-1536
	v_lshl_add_u64 v[0:1], v[20:21], 0, s[38:39]
	s_or_b32 s38, s22, 6
	s_ashr_i32 s39, s38, 31
	s_lshl_b64 s[38:39], s[38:39], 9
	v_cvt_pk_bf16_f32 v2, v81, v86
	global_store_dword v[0:1], v2, off offset:-1536
	v_lshl_add_u64 v[0:1], v[20:21], 0, s[38:39]
	s_or_b32 s38, s22, 7
	s_ashr_i32 s39, s38, 31
	v_cvt_pk_bf16_f32 v2, v88, v89
	s_lshl_b64 s[38:39], s[38:39], 9
	global_store_dword v[0:1], v2, off offset:-1536
	v_cvt_pk_bf16_f32 v2, v44, v46
	v_lshl_add_u64 v[0:1], v[20:21], 0, s[38:39]
	global_store_dword v[0:1], v2, off offset:-1536

; __device__ __forceinline__ float silu_f(float x) { return x * __builtin_amdgcn_rcpf(1.0f + __builtin_amdgcn_exp2f(-1.4426950408889634f * x)); }
; __device__ __forceinline__ float bflo(unsigned x) { return __uint_as_float(x << 16); }
; __device__ __forceinline__ float bfhi(unsigned x) { return __uint_as_float(x & 0xffff0000u); }
; __device__ __forceinline__ unsigned pk2(float lo, float hi) { return pg8::cvt_pk_bf16(lo, hi); }
; __device__ __forceinline__ float silu_f(float x) { return x * __builtin_amdgcn_rcpf(1.0f + __builtin_amdgcn_exp2f(-1.4426950408889634f * x)); }
; __device__ __forceinline__ void ph_conv(const bf16* XBC, const float* state_conv, const float* conv_w, const float* conv_b, bf16* XT, bf16* BN, bf16* CN, bf16* BT, int c_lo, int c_hi, int vcu, int G, int tid) {
;     ...
;         for (int t8 = 0; t8 < 2; ++t8) {
;             float y0[8], y1[8];
; #pragma unroll
;             for (int i = 0; i < 8; ++i) { const float x0 = bflo(raw[3 + t8 * 8 + i]), x1 = bfhi(raw[3 + t8 * 8 + i]);
;                 const float a0 = b0 + w0[0] * p0[0] + w0[1] * p0[1] + w0[2] * p0[2] + w0[3] * x0, a1 = b1 + w1[0] * p1[0] + w1[1] * p1[1] + w1[2] * p1[2] + w1[3] * x1;
;                 y0[i] = silu_f(a0); y1[i] = silu_f(a1); p0[0] = p0[1]; p0[1] = p0[2]; p0[2] = x0; p1[0] = p1[1]; p1[1] = p1[2]; p1[2] = x1; }
;             v4u t0, t1; t0.x = pk2(y0[0], y0[1]); t0.y = pk2(y0[2], y0[3]); t0.z = pk2(y0[4], y0[5]); t0.w = pk2(y0[6], y0[7]);
;             t1.x = pk2(y1[0], y1[1]); t1.y = pk2(y1[2], y1[3]); t1.z = pk2(y1[4], y1[5]); t1.w = pk2(y1[6], y1[7]);
.LBB0_809:
	s_or_b64 exec, exec, s[24:25]
	s_nop 0
	v_lshlrev_b32_e32 v1, 16, v78
	v_fma_f32 v0, v35, v43, v18
	v_fma_f32 v2, v34, v42, v0
	v_mov_b32_e32 v0, v47
	v_and_b32_e32 v3, 0xffff0000, v78
	v_fma_f32 v0, v12, v0, v2
	v_fma_f32 v0, v13, v1, v0
	v_mov_b32_e32 v7, v42
	v_fma_f32 v2, v31, v41, v19
	v_fma_f32 v6, v30, v40, v2
	v_mov_b32_e32 v2, v45
	v_mov_b32_e32 v46, v1
	v_fma_f32 v2, v28, v2, v6
	v_mul_f32_e32 v4, 0xbfb8aa3b, v0
	v_exp_f32_e32 v4, v4
	v_fma_f32 v2, v29, v3, v2
	v_mul_f32_e32 v5, 0xbfb8aa3b, v2
	v_exp_f32_e32 v5, v5
	v_add_f32_e32 v4, 1.0, v4
	v_rcp_f32_e32 v4, v4
	v_mov_b32_e32 v6, v47
	v_add_f32_e32 v5, 1.0, v5
	v_rcp_f32_e32 v5, v5
	v_mul_f32_e32 v41, v0, v4
	v_fma_f32 v0, v35, v7, v18
	v_fma_f32 v0, v34, v6, v0
	v_mov_b32_e32 v6, v45
	v_mov_b32_e32 v7, v40
	v_mul_f32_e32 v43, v2, v5
	v_fma_f32 v2, v31, v7, v19
	v_fma_f32 v2, v30, v6, v2
	v_mov_b32_e32 v44, v3
	v_fma_f32 v7, v35, v47, v18
	v_lshlrev_b32_e32 v47, 16, v77
	v_fma_f32 v40, v34, v46, v7
	v_pk_mul_f32 v[6:7], v[30:31], v[44:45]
	v_mov_b32_e32 v44, v1
	v_mov_b32_e32 v45, v47
	v_lshlrev_b32_e32 v46, 16, v76
	v_fma_f32 v0, v12, v44, v0
	v_fma_f32 v0, v13, v45, v0
	v_mul_f32_e32 v42, 0xbfb8aa3b, v0
	v_exp_f32_e32 v42, v42
	v_add_f32_e32 v7, v19, v7
	v_and_b32_e32 v5, 0xffff0000, v77
	v_fma_f32 v40, v11, v47, v40
	v_add_f32_e32 v45, v6, v7
	v_add_f32_e32 v6, 1.0, v42
	v_rcp_f32_e32 v42, v6
	v_fma_f32 v40, v10, v46, v40
	v_mul_f32_e32 v44, 0xbfb8aa3b, v40
	v_exp_f32_e32 v44, v44
	v_mul_f32_e32 v42, v0, v42
	v_mov_b32_e32 v0, v47
	v_add_f32_e32 v6, 1.0, v44
	v_fma_f32 v1, v35, v1, v18
	v_fma_f32 v77, v34, v0, v1
	v_mov_b32_e32 v0, v3
	v_mov_b32_e32 v1, v5
	v_rcp_f32_e32 v44, v6
	v_and_b32_e32 v4, 0xffff0000, v76
	v_fma_f32 v0, v28, v0, v2
	v_fma_f32 v2, v29, v1, v0
	v_mul_f32_e32 v0, 0xbfb8aa3b, v2
	v_mul_f32_e32 v40, v40, v44
	v_exp_f32_e32 v44, v0
	v_and_b32_e32 v7, 0xffff0000, v75
	v_fma_f32 v1, v33, v5, v45
	v_fma_f32 v45, v32, v4, v1
	v_mul_f32_e32 v0, 0xbfb8aa3b, v45
	v_exp_f32_e32 v76, v0
	v_add_f32_e32 v44, 1.0, v44
	v_rcp_f32_e32 v44, v44
	v_add_f32_e32 v76, 1.0, v76
	v_rcp_f32_e32 v78, v76
	v_fma_f32 v1, v35, v47, v18
	v_mul_f32_e32 v76, v2, v44
	v_mov_b32_e32 v2, v5
	v_fma_f32 v80, v34, v46, v1
	v_pk_mul_f32 v[0:1], v[30:31], v[2:3]
	v_lshlrev_b32_e32 v3, 16, v75
	v_mul_f32_e32 v44, v45, v78
	v_mov_b32_e32 v78, v46
	v_mov_b32_e32 v79, v3
	v_add_f32_e32 v1, v19, v1
	v_fma_f32 v2, v12, v78, v77
	v_fma_f32 v45, v13, v79, v2
	v_mul_f32_e32 v2, 0xbfb8aa3b, v45
	v_exp_f32_e32 v75, v2
	v_add_f32_e32 v81, v0, v1
	v_lshlrev_b32_e32 v2, 16, v74
	v_fma_f32 v1, v31, v5, v19
	v_fma_f32 v77, v30, v4, v1
	v_add_f32_e32 v0, 1.0, v75
	v_and_b32_e32 v6, 0xffff0000, v74
	v_rcp_f32_e32 v74, v0
	v_pk_mov_b32 v[46:47], v[2:3], v[46:47] op_sel:[1,0]
	v_fma_f32 v1, v11, v3, v80
	v_fma_f32 v79, v10, v2, v1
	v_mul_f32_e32 v0, 0xbfb8aa3b, v79
	v_exp_f32_e32 v75, v0
	v_mul_f32_e32 v45, v45, v74
	v_lshlrev_b32_e32 v78, 16, v73
	v_add_f32_e32 v74, 1.0, v75
	v_rcp_f32_e32 v80, v74
	v_fma_f32 v47, v35, v47, v18
	v_pk_mul_f32 v[74:75], v[34:35], v[2:3]
	v_mov_b32_e32 v3, v78
	v_fma_f32 v82, v34, v46, v47
	v_pk_mul_f32 v[46:47], v[12:13], v[2:3]
	v_and_b32_e32 v0, 0xffff0000, v73
	v_add_f32_e32 v3, v46, v82
	v_add_f32_e32 v3, v3, v47
	v_mul_f32_e32 v46, 0xbfb8aa3b, v3
	v_add_f32_e32 v73, v18, v75
	v_exp_f32_e32 v46, v46
	v_mul_f32_e32 v47, v79, v80
	v_add_f32_e32 v80, v74, v73
	v_mov_b32_e32 v74, v4
	v_mov_b32_e32 v75, v7
	v_add_f32_e32 v46, 1.0, v46
	v_fma_f32 v73, v28, v74, v81
	v_fma_f32 v81, v29, v75, v73
	v_mul_f32_e32 v73, 0xbfb8aa3b, v81
	v_rcp_f32_e32 v46, v46
	v_exp_f32_e32 v74, v73
	v_lshlrev_b32_e32 v79, 16, v72
	v_pk_mov_b32 v[4:5], v[6:7], v[4:5] op_sel:[1,0]
	v_mul_f32_e32 v46, v3, v46
	v_add_f32_e32 v3, 1.0, v74
	v_rcp_f32_e32 v3, v3
	v_fma_f32 v75, v33, v7, v77
	v_fma_f32 v77, v32, v6, v75
	v_mul_f32_e32 v74, 0xbfb8aa3b, v77
	v_exp_f32_e32 v74, v74
	v_and_b32_e32 v1, 0xffff0000, v72
	v_fma_f32 v72, v12, v78, v80
	v_fma_f32 v5, v31, v5, v19
	v_fma_f32 v82, v13, v79, v72
	v_fma_f32 v72, v30, v4, v5
	v_pk_mul_f32 v[4:5], v[30:31], v[6:7]
	v_mov_b32_e32 v7, v0
	v_mul_f32_e32 v73, v81, v3
	v_add_f32_e32 v3, 1.0, v74
	v_pk_mul_f32 v[74:75], v[28:29], v[6:7]
	v_rcp_f32_e32 v3, v3
	v_add_f32_e32 v7, v74, v72
	v_add_f32_e32 v7, v7, v75
	v_mul_f32_e32 v72, 0xbfb8aa3b, v7
	v_exp_f32_e32 v72, v72
	v_mul_f32_e32 v75, v77, v3
	v_add_f32_e32 v3, v19, v5
	v_add_f32_e32 v3, v4, v3
	v_add_f32_e32 v4, 1.0, v72
	v_rcp_f32_e32 v72, v4
	v_mov_b32_e32 v80, v78
	v_fma_f32 v3, v28, v0, v3
	v_fma_f32 v74, v29, v1, v3
	v_mul_f32_e32 v3, 0xbfb8aa3b, v82
	v_exp_f32_e32 v3, v3
	v_mul_f32_e32 v4, 0xbfb8aa3b, v74
	v_exp_f32_e32 v4, v4
	v_mov_b32_e32 v81, v2
	v_pk_mul_f32 v[80:81], v[34:35], v[80:81]
	v_add_f32_e32 v3, 1.0, v3
	v_add_f32_e32 v2, v18, v81
	v_mul_f32_e32 v72, v7, v72
	v_rcp_f32_e32 v7, v3
	v_add_f32_e32 v77, 1.0, v4
	v_lshlrev_b32_e32 v3, 16, v71
	v_add_f32_e32 v4, v80, v2
	v_mov_b32_e32 v2, v79
	v_and_b32_e32 v5, 0xffff0000, v71
	v_fma_f32 v2, v12, v2, v4
	v_fma_f32 v71, v13, v3, v2
	v_mov_b32_e32 v2, v0
	v_mov_b32_e32 v3, v6
	v_mov_b32_e32 v4, v1
	v_fma_f32 v0, v31, v3, v19
	v_fma_f32 v2, v30, v2, v0
	v_rcp_f32_e32 v3, v77
	v_fma_f32 v0, v28, v4, v2
	v_fma_f32 v0, v29, v5, v0
	v_mul_f32_e32 v1, 0xbfb8aa3b, v71
	v_mul_f32_e32 v2, 0xbfb8aa3b, v0
	v_exp_f32_e32 v1, v1
	v_exp_f32_e32 v2, v2
	v_mul_f32_e32 v77, v82, v7
	v_mul_f32_e32 v78, v74, v3
	v_add_f32_e32 v1, 1.0, v1
	v_add_f32_e32 v2, 1.0, v2
	v_rcp_f32_e32 v1, v1
	v_rcp_f32_e32 v2, v2
	v_mul_f32_e32 v71, v71, v1
	v_mul_f32_e32 v74, v0, v2
	v_cvt_pk_bf16_f32 v0, v41, v42
	v_cvt_pk_bf16_f32 v1, v40, v45
	v_cvt_pk_bf16_f32 v2, v47, v46
	v_cvt_pk_bf16_f32 v3, v77, v71
	v_cvt_pk_bf16_f32 v4, v43, v76
	v_cvt_pk_bf16_f32 v5, v44, v73
	v_cvt_pk_bf16_f32 v6, v75, v72
	v_cvt_pk_bf16_f32 v7, v78, v74
	s_and_saveexec_b64 s[24:25], s[2:3]
	s_xor_b64 s[24:25], exec, s[24:25]
	s_cbranch_execz .LBB0_815
; __device__ __forceinline__ unsigned pk2(float lo, float hi) { return pg8::cvt_pk_bf16(lo, hi); }
; __device__ __forceinline__ void ph_conv(const bf16* XBC, const float* state_conv, const float* conv_w, const float* conv_b, bf16* XT, bf16* BN, bf16* CN, bf16* BT, int c_lo, int c_hi, int vcu, int G, int tid) {
;     ...
;             else if (tid < 384) { const int cb = ch - 512, g = cb >> 7, n = cb & 127;
; #pragma unroll
;                 for (int i = 0; i < 8; ++i) *(unsigned*)(BN + (size_t)(row0 + t8 * 8 + i) * 256 + cb) = pk2(y0[i], y1[i]);
;                 bf16* d = BT + ((size_t)(ci * 2 + g) * 128 + n) * 64 + tl; *(v4u*)d = t0; *(v4u*)(d + 64) = t1; }
;             else { const int cc = ch - 768;
; #pragma unroll
;                 for (int i = 0; i < 8; ++i) *(unsigned*)(CN + (size_t)(row0 + t8 * 8 + i) * 256 + cc) = pk2(y0[i], y1[i]); }
	s_or_b32 s26, s22, 8
	s_ashr_i32 s27, s26, 31
	s_lshl_b64 s[26:27], s[26:27], 9
	s_and_saveexec_b64 s[28:29], s[4:5]
	s_xor_b64 s[28:29], exec, s[28:29]
	s_cbranch_execz .LBB0_812
	s_or_b32 s38, s22, 9
	s_ashr_i32 s39, s38, 31
	v_lshl_add_u64 v[0:1], v[20:21], 0, s[26:27]
	s_lshl_b64 s[38:39], s[38:39], 9
	v_cvt_pk_bf16_f32 v2, v41, v43
	global_store_dword v[0:1], v2, off offset:-1536
	v_lshl_add_u64 v[0:1], v[20:21], 0, s[38:39]
	s_or_b32 s38, s22, 10
	s_ashr_i32 s39, s38, 31
	s_lshl_b64 s[38:39], s[38:39], 9
	v_cvt_pk_bf16_f32 v2, v42, v76
	global_store_dword v[0:1], v2, off offset:-1536
	v_lshl_add_u64 v[0:1], v[20:21], 0, s[38:39]
	s_or_b32 s38, s22, 11
	s_ashr_i32 s39, s38, 31
	s_lshl_b64 s[38:39], s[38:39], 9
	v_cvt_pk_bf16_f32 v2, v40, v44
	global_store_dword v[0:1], v2, off offset:-1536
	v_lshl_add_u64 v[0:1], v[20:21], 0, s[38:39]
	s_or_b32 s38, s22, 12
	s_ashr_i32 s39, s38, 31
	s_lshl_b64 s[38:39], s[38:39], 9
	v_cvt_pk_bf16_f32 v2, v45, v73
	global_store_dword v[0:1], v2, off offset:-1536
	v_lshl_add_u64 v[0:1], v[20:21], 0, s[38:39]
	s_or_b32 s38, s22, 13
	s_ashr_i32 s39, s38, 31
	s_lshl_b64 s[38:39], s[38:39], 9
	v_cvt_pk_bf16_f32 v2, v47, v75
	global_store_dword v[0:1], v2, off offset:-1536
	v_lshl_add_u64 v[0:1], v[20:21], 0, s[38:39]
	s_or_b32 s38, s22, 14
	s_ashr_i32 s39, s38, 31
	s_lshl_b64 s[38:39], s[38:39], 9
	v_cvt_pk_bf16_f32 v2, v46, v72
	global_store_dword v[0:1], v2, off offset:-1536
	v_lshl_add_u64 v[0:1], v[20:21], 0, s[38:39]
	s_or_b32 s38, s22, 15
	s_ashr_i32 s39, s38, 31
	v_cvt_pk_bf16_f32 v2, v77, v78
	s_lshl_b64 s[38:39], s[38:39], 9
	global_store_dword v[0:1], v2, off offset:-1536
	v_cvt_pk_bf16_f32 v2, v71, v74
	v_lshl_add_u64 v[0:1], v[20:21], 0, s[38:39]
	global_store_dword v[0:1], v2, off offset:-1536
